# prologue x->bf16 rows: 64-lane sum of squares via four DPP row_ror adds and two permlane swaps instead of six serial ds_bpermute round trips
# speedup vs baseline: 1.0043x; 1.0043x over previous
.LBB0_200:
	global_load_dwordx4 v[4:7], v[22:23], off offset:-3072
	global_load_dwordx4 v[0:3], v[22:23], off offset:-2048
	global_load_dwordx4 v[8:11], v[22:23], off offset:-1024
	global_load_dwordx4 v[12:15], v[22:23], off
	s_waitcnt vmcnt(0)
	v_mul_f32_e32 v17, v5, v5
	v_mul_f32_e32 v30, v7, v7
	v_mul_f32_e32 v31, v1, v1
	v_mul_f32_e32 v33, v3, v3
	v_mul_f32_e32 v34, v9, v9
	v_mul_f32_e32 v35, v11, v11
	v_fmac_f32_e32 v17, v4, v4
	v_fmac_f32_e32 v30, v6, v6
	v_fmac_f32_e32 v31, v0, v0
	v_fmac_f32_e32 v33, v2, v2
	v_mul_f32_e32 v36, v13, v13
	v_mul_f32_e32 v37, v15, v15
	v_fmac_f32_e32 v34, v8, v8
	v_fmac_f32_e32 v35, v10, v10
	v_add_f32_e32 v17, v17, v30
	v_add_f32_e32 v30, v31, v33
	v_fmac_f32_e32 v36, v12, v12
	v_fmac_f32_e32 v37, v14, v14
	v_add_f32_e32 v31, v34, v35
	v_add_f32_e32 v17, v17, v30
	v_add_f32_e32 v17, v17, v31
	v_add_f32_e32 v30, v36, v37
	v_add_f32_e32 v17, v17, v30
	s_nop 1
	v_add_f32_dpp v17, v17, v17 row_ror:1 row_mask:0xf bank_mask:0xf
	s_nop 1
	v_add_f32_dpp v17, v17, v17 row_ror:2 row_mask:0xf bank_mask:0xf
	s_nop 1
	v_add_f32_dpp v17, v17, v17 row_ror:4 row_mask:0xf bank_mask:0xf
	s_nop 1
	v_add_f32_dpp v17, v17, v17 row_ror:8 row_mask:0xf bank_mask:0xf
	v_mov_b32_e32 v30, v17
	s_nop 1
	v_permlane16_swap_b32 v30, v17
	v_add_f32_e32 v17, v17, v30
	v_mov_b32_e32 v30, v17
	s_nop 1
	v_permlane32_swap_b32 v30, v17
	s_and_saveexec_b64 s[20:21], s[4:5]
	s_cbranch_execz .LBB0_199
	s_waitcnt lgkmcnt(0)
	v_add_f32_e32 v17, v17, v30
	v_cndmask_b32_e64 v17, 0, v17, s[6:7]
	v_lshl_add_u64 v[30:31], s[38:39], 0, v[18:19]
	global_store_dword v[30:31], v17, off
	s_branch .LBB0_199
